# prio
# speedup vs baseline: 1.0046x; 1.0046x over previous
; template <int DQK, int NQ, int MODE, int CH> ...
;     ...
;   f32x4 o[4][NQ];
;   float mrun[NQ], lsum[NQ];
; #pragma unroll
;   for (int nq = 0; nq < NQ; ++nq) {
; #pragma unroll
;     for (int md = 0; md < 4; ++md) o[md][nq] = f32x4{0.f, 0.f, 0.f, 0.f};
;     if (MODE == 0) { mrun[nq] = sink2; lsum[nq] = (fq == 0) ? 1.0f : 0.0f; }
;     else { mrun[nq] = NEGBIG; lsum[nq] = 0.f; }
;   }
;     ...
;   __syncthreads();
;   LOAD_CHUNK(kt_lo);
;   STORE_CHUNK(0);
;   __syncthreads();
;   int buf = 0;
;   for (int kt0 = kt_lo; kt0 < kt_hi; kt0 += CH) {
;     if (kt0 + CH < kt_hi) LOAD_CHUNK(kt0 + CH);
.LBB0_826:
	s_or_b64 exec, exec, s[34:35]
	s_movk_i32 s30, 0x68
	v_mul_lo_u32 v2, v50, s30
	v_lshlrev_b32_e32 v1, 3, v48
	v_lshlrev_b32_e32 v124, 1, v2
	v_lshlrev_b32_e32 v125, 1, v40
	v_add3_u32 v2, 0, v124, v125
	s_movk_i32 s30, 0x90
	v_and_b32_e32 v1, 32, v1
	s_waitcnt vmcnt(1)
	ds_write_b128 v2, v[36:39]
	v_mul_lo_u32 v2, v46, s30
	v_lshlrev_b32_e32 v1, 1, v1
	v_add3_u32 v1, 0, v2, v1
	v_lshlrev_b32_e32 v2, 2, v48
	v_lshlrev_b32_e32 v3, 5, v48
	v_and_b32_e32 v2, 8, v2
	v_and_b32_e32 v3, 32, v3
	v_add3_u32 v126, v1, v2, v3
	v_add_u32_e32 v1, 0x6800, v126
	v_lshlrev_b32_e32 v127, 4, v51
	s_waitcnt vmcnt(0)
	ds_write2_b64 v1, v[32:33], v[34:35] offset1:2
	s_and_saveexec_b64 s[30:31], s[2:3]
	s_xor_b64 s[2:3], exec, s[30:31]
	v_lshlrev_b32_e32 v127, 4, v51
	s_or_saveexec_b64 s[2:3], s[2:3]
	s_movk_i32 s30, 0xd0
	v_mul_lo_u32 v128, v47, s30
	s_xor_b64 exec, exec, s[2:3]
	v_add3_u32 v1, 0, v128, v127
	ds_write_b128 v1, v[28:31]
	s_or_b64 exec, exec, s[2:3]
	v_mov_b64_e32 v[2:3], s[28:29]
	v_mad_i64_i32 v[2:3], s[2:3], v47, s79, v[2:3]
	v_mad_i64_i32 v[32:33], s[2:3], v50, s79, 0
	v_mad_u64_u32 v[2:3], s[2:3], s0, v122, v[2:3]
	s_add_i32 s2, s21, s0
	s_ashr_i32 s3, s2, 31
	s_lshl_b64 s[2:3], s[2:3], 19
	v_and_b32_e32 v36, 7, v48
	v_lshl_add_u64 v[32:33], s[28:29], 0, v[32:33]
	v_lshl_add_u64 v[34:35], s[2:3], 0, v[42:43]
	v_lshlrev_b32_e32 v36, 4, v36
	v_mov_b32_e32 v37, v0
	v_mad_u64_u32 v[32:33], s[2:3], s0, v122, v[32:33]
	v_lshl_add_u64 v[2:3], v[44:45], 1, v[2:3]
	v_lshl_add_u64 v[34:35], v[34:35], 0, v[36:37]
	v_lshl_add_u64 v[32:33], v[40:41], 1, v[32:33]
	v_mov_b32_e32 v44, 0
	v_ashrrev_i32_e32 v75, 31, v74
	v_ashrrev_i32_e32 v73, 31, v72
	v_lshl_add_u32 v1, v89, 4, 0
	v_mul_u32_u24_e32 v129, 0xd0, v49
	v_mul_u32_u24_e32 v123, 0x90, v49
	v_lshl_add_u64 v[2:3], s[24:25], 0, v[2:3]
	v_lshl_add_u64 v[78:79], s[14:15], 0, v[34:35]
	v_lshl_add_u64 v[80:81], s[24:25], 0, v[32:33]
	v_mov_b32_e32 v82, 0xf149f2ca
	s_mov_b32 s30, 0
	s_mov_b64 s[2:3], 0
	v_mov_b32_e32 v45, v44
	v_mov_b32_e32 v46, v44
	v_mov_b32_e32 v47, v44
	v_mov_b32_e32 v60, v44
	v_mov_b32_e32 v61, v44
	v_mov_b32_e32 v62, v44
	v_mov_b32_e32 v63, v44
	v_mov_b32_e32 v36, v44
	v_mov_b32_e32 v37, v44
	v_mov_b32_e32 v38, v44
	v_mov_b32_e32 v39, v44
	v_mov_b32_e32 v52, v44
	v_mov_b32_e32 v53, v44
	v_mov_b32_e32 v54, v44
	v_mov_b32_e32 v55, v44
	v_mov_b32_e32 v40, v44
	v_mov_b32_e32 v41, v44
	v_mov_b32_e32 v42, v44
	v_mov_b32_e32 v43, v44
	v_mov_b32_e32 v56, v44
	v_mov_b32_e32 v57, v44
	v_mov_b32_e32 v58, v44
	v_mov_b32_e32 v59, v44
	v_mov_b32_e32 v32, v44
	v_mov_b32_e32 v33, v44
	v_mov_b32_e32 v34, v44
	v_mov_b32_e32 v35, v44
	v_mov_b32_e32 v48, v44
	v_mov_b32_e32 v49, v44
	v_mov_b32_e32 v50, v44
	v_mov_b32_e32 v51, v44
	v_mov_b32_e32 v76, v44
	v_mov_b32_e32 v77, v44
	v_mov_b32_e32 v83, 0xf149f2ca
	s_waitcnt lgkmcnt(0)
	s_barrier
	v_readfirstlane_b32 s98, v214
	s_nop 3
	s_cmp_ge_u32 s98, 0x100
	s_cbranch_scc0 .Lprio_done_mla
	s_setprio 1
.Lprio_done_mla:
	v_lshl_add_u64 v[64:65], v[80:81], 0, s[2:3]
	global_load_dwordx4 v[68:71], v[64:65], off
	s_nop 0
	global_load_dwordx4 v[64:67], v[78:79], off
	s_and_saveexec_b64 s[28:29], vcc
	v_lshl_add_u64 v[28:29], v[2:3], 0, s[2:3]
	global_load_dwordx4 v[28:31], v[28:29], off
	s_or_b64 exec, exec, s[28:29]
	s_mov_b64 s[28:29], 0x18000
	v_lshl_add_u64 v[80:81], v[80:81], 0, s[28:29]
	v_lshl_add_u64 v[2:3], v[2:3], 0, s[28:29]
	s_mov_b64 s[28:29], 0x80
	v_lshl_add_u64 v[78:79], v[78:79], 0, s[28:29]

; template <int DQK, int NQ, int MODE, int CH> ...
;     ...
;   if (MODE == 2) {
; #pragma unroll
;     for (int nq = 0; nq < NQ; ++nq) {
;       const int c = c0 + nq * 16 + fr;
;       const int cs = min(max(c - 8, 0), 48);
; #pragma unroll
;       for (int mk = 0; mk < 4; ++mk)
; #pragma unroll
;         for (int j = 0; j < 4; ++j) {
;           const int x = mk * 16 + fq * 4 + j;
;           dci[nq][mk][j] = min(max(x - c + 15, 0), 30);
;           pen[nq][mk][j] = ((x >= cs) && (x < cs + 16)) ? 0.f : NEGBIG;
;         }
;     }
;   }
; DEVI void ph_natten(const Params& p, char* shm) {
;     ...
;     for (int i = tid; i < 465; i += NTHR) bias_s[i] = rpb[h * 465 + i] * LOG2E;
.LBB0_1528:
	v_readlane_b32 s98, v242, 28
	v_readlane_b32 s99, v242, 29
	v_mov_b32_e32 v225, s62
	v_mul_u32_u24_e32 v225, 0x1d1, v225
	v_add_u32_e32 v225, v225, v214
	v_lshlrev_b32_e32 v225, 2, v225
	s_and_saveexec_b64 vcc, s[66:67]
	s_nop 0
	global_load_dword v225, v225, s[98:99]
	s_mov_b64 exec, vcc
	v_mul_lo_u32 v3, v48, s13
	v_lshlrev_b32_e32 v1, 3, v52
	v_lshlrev_b32_e32 v151, 1, v3
	v_lshlrev_b32_e32 v3, 1, v52
	v_and_b32_e32 v1, 32, v1
	v_and_b32_e32 v3, 4, v3
	v_lshlrev_b32_e32 v152, 1, v1
	v_lshlrev_b32_e32 v153, 1, v3
	v_and_b32_e32 v3, 16, v49
	v_mul_lo_u32 v2, v54, s13
	v_add3_u32 v1, 0, v151, v152
	v_lshlrev_b32_e32 v154, 1, v3
	v_lshlrev_b32_e32 v149, 1, v2
	v_lshlrev_b32_e32 v150, 1, v46
	v_add3_u32 v1, v1, v153, v154
	v_add3_u32 v2, 0, v149, v150
	v_add_u32_e32 v3, 0xd800, v1
	v_add_u32_e32 v1, 0xf800, v1
	v_mov_b32_e32 v221, v2
	v_mov_b32_e32 v222, v3
	v_mov_b32_e32 v223, v1
	v_add3_u32 v1, s14, v151, v152
	v_lshlrev_b32_e32 v148, 2, v53
	v_add3_u32 v1, v1, v153, v154
	v_mov_b32_e32 v224, v1
	s_cmp_lt_i32 s60, -11
	s_cbranch_scc1 .Lna_skip_fill
	v_lshrrev_b32_e32 v1, 31, v52
	v_add_u32_e32 v1, v55, v1
	v_ashrrev_i32_e32 v56, 1, v1
	v_and_b32_e32 v1, -2, v1
	v_sub_u32_e32 v48, v55, v1
	v_lshlrev_b32_e32 v1, 5, v48
	v_or_b32_e32 v3, 23, v1
	v_or_b32_e32 v1, v1, v50
	v_max_i32_e32 v49, 8, v1
	v_add_u32_e32 v49, -8, v49
	v_add_u32_e32 v2, s20, v56
	v_min_u32_e32 v49, 48, v49
	v_or_b32_e32 v60, 1, v148
	v_max_i32_e32 v2, 4, v2
	v_min_i32_e32 v3, 48, v3
	v_mov_b32_e32 v207, 0xf149f2ca
	v_cmp_lt_u32_e64 s[16:17], v60, v49
	v_or_b32_e32 v61, 16, v148
	v_add_u32_e32 v2, -4, v2
	v_add_u32_e32 v57, 15, v3
	v_add_u32_e32 v58, 16, v49
	v_cmp_lt_u32_e32 vcc, v148, v49
	v_cndmask_b32_e64 v3, 0, v207, s[16:17]
	v_cmp_ge_u32_e64 s[16:17], v61, v49
	v_or_b32_e32 v62, 17, v148
	v_min_u32_e32 v155, 56, v2
	v_cndmask_b32_e32 v2, 0, v207, vcc
	s_and_b64 s[4:5], s[16:17], vcc
	v_cmp_ge_u32_e32 vcc, v62, v49
	v_cmp_lt_u32_e64 s[16:17], v62, v58
	v_or_b32_e32 v63, 18, v148
	v_cndmask_b32_e64 v156, v207, 0, s[4:5]
	s_and_b64 s[4:5], vcc, s[16:17]
	v_cmp_ge_u32_e32 vcc, v63, v49
	v_cmp_lt_u32_e64 s[16:17], v63, v58
	v_or_b32_e32 v64, 19, v148
	v_cndmask_b32_e64 v157, v207, 0, s[4:5]
	s_and_b64 s[4:5], vcc, s[16:17]
	v_cmp_ge_u32_e32 vcc, v64, v49
	v_cmp_lt_u32_e64 s[16:17], v64, v58
	v_or_b32_e32 v65, 32, v148
	v_or_b32_e32 v1, 16, v1
	v_cndmask_b32_e64 v158, v207, 0, s[4:5]
	s_and_b64 s[4:5], vcc, s[16:17]
	v_cmp_ge_u32_e32 vcc, v65, v49
	v_cmp_lt_u32_e64 s[16:17], v65, v58
	v_or_b32_e32 v66, 33, v148
	v_max_i32_e32 v1, 8, v1
	v_cndmask_b32_e64 v159, v207, 0, s[4:5]
	s_and_b64 s[4:5], vcc, s[16:17]
	v_cmp_ge_u32_e32 vcc, v66, v49
	v_cmp_lt_u32_e64 s[16:17], v66, v58
	v_or_b32_e32 v67, 34, v148
	v_add_u32_e32 v1, -8, v1
	v_cndmask_b32_e64 v160, v207, 0, s[4:5]
	s_and_b64 s[4:5], vcc, s[16:17]
	v_cmp_ge_u32_e32 vcc, v67, v49
	v_cmp_lt_u32_e64 s[16:17], v67, v58
	v_or_b32_e32 v68, 35, v148
	v_min_u32_e32 v55, 48, v1
	v_cndmask_b32_e64 v161, v207, 0, s[4:5]
	s_and_b64 s[4:5], vcc, s[16:17]
	v_cmp_ge_u32_e32 vcc, v68, v49
	v_cmp_lt_u32_e64 s[16:17], v68, v58
	v_cndmask_b32_e64 v162, v207, 0, s[4:5]
	s_and_b64 s[4:5], vcc, s[16:17]
	v_cmp_lt_u32_e64 s[16:17], v60, v55
	v_or_b32_e32 v60, 3, v148
	v_or_b32_e32 v69, 2, v148
	v_cndmask_b32_e64 v115, 0, v207, s[16:17]
	v_cmp_lt_u32_e64 s[16:17], v60, v49
	v_add_u32_e32 v59, 16, v55
	v_cmp_lt_u32_e32 vcc, v148, v55
	v_cndmask_b32_e64 v117, 0, v207, s[16:17]
	v_cmp_lt_u32_e64 s[16:17], v69, v49
	v_cndmask_b32_e64 v163, v207, 0, s[4:5]
	v_cndmask_b32_e32 v114, 0, v207, vcc
	v_cndmask_b32_e64 v116, 0, v207, s[16:17]
	v_cmp_lt_u32_e64 s[16:17], v60, v55
	s_bfe_u32 s18, s97, 0x40002
	s_lshl_b32 s0, s18, 2
	v_cndmask_b32_e64 v119, 0, v207, s[16:17]
	v_cmp_lt_u32_e64 s[16:17], v69, v55
	s_max_u32 s45, s0, 4
	s_lshr_b32 s0, s39, 4
	v_cndmask_b32_e64 v118, 0, v207, s[16:17]
	v_cmp_ge_u32_e64 s[16:17], v61, v55
	s_and_b64 s[4:5], s[16:17], vcc
	v_cmp_ge_u32_e32 vcc, v62, v55
	v_cmp_lt_u32_e64 s[16:17], v62, v59
	v_cndmask_b32_e64 v164, v207, 0, s[4:5]
	s_and_b64 s[4:5], vcc, s[16:17]
	v_cmp_ge_u32_e32 vcc, v63, v55
	v_cmp_lt_u32_e64 s[16:17], v63, v59
	v_cndmask_b32_e64 v165, v207, 0, s[4:5]
	s_and_b64 s[4:5], vcc, s[16:17]
	v_cmp_ge_u32_e32 vcc, v64, v55
	v_cmp_lt_u32_e64 s[16:17], v64, v59
	v_cndmask_b32_e64 v166, v207, 0, s[4:5]
	s_and_b64 s[4:5], vcc, s[16:17]
	v_cmp_ge_u32_e32 vcc, v65, v55
	v_cmp_lt_u32_e64 s[16:17], v65, v59
	v_cndmask_b32_e64 v167, v207, 0, s[4:5]
	s_and_b64 s[4:5], vcc, s[16:17]
	v_cmp_ge_u32_e32 vcc, v66, v55
	v_cmp_lt_u32_e64 s[16:17], v66, v59
	v_cndmask_b32_e64 v168, v207, 0, s[4:5]
	s_and_b64 s[4:5], vcc, s[16:17]
	v_cmp_ge_u32_e32 vcc, v67, v55
	v_cmp_lt_u32_e64 s[16:17], v67, v59
	v_cndmask_b32_e64 v169, v207, 0, s[4:5]
	s_and_b64 s[4:5], vcc, s[16:17]
	v_cmp_ge_u32_e32 vcc, v68, v55
	v_cmp_lt_u32_e64 s[16:17], v68, v59
	v_or_b32_e32 v62, 49, v148
	v_cndmask_b32_e64 v170, v207, 0, s[4:5]
	s_and_b64 s[4:5], vcc, s[16:17]
	v_or_b32_e32 v63, 48, v148
	v_cmp_lt_u32_e32 vcc, v62, v58
	v_or_b32_e32 v64, 51, v148
	v_or_b32_e32 v65, 50, v148
	v_cndmask_b32_e64 v121, v207, 0, vcc
	v_cmp_lt_u32_e32 vcc, v63, v58
	v_ashrrev_i32_e32 v49, 4, v57
	v_cndmask_b32_e64 v171, v207, 0, s[4:5]
	v_cndmask_b32_e64 v120, v207, 0, vcc
	v_cmp_lt_u32_e32 vcc, v62, v59
	s_and_b32 s4, s0, 15
	s_lshl_b32 s0, s45, 7
	v_cndmask_b32_e64 v123, v207, 0, vcc
	v_cmp_lt_u32_e32 vcc, v63, v59
	v_cmp_lt_i32_e64 s[16:17], -1, v49
	s_addk_i32 s0, 0xfe00
	v_cndmask_b32_e64 v122, v207, 0, vcc
	v_cmp_lt_u32_e32 vcc, v64, v58
	s_add_i32 s60, s60, 12
	s_mul_i32 s33, s18, 0x1f0
	v_cndmask_b32_e64 v125, v207, 0, vcc
; template <int DQK, int NQ, int MODE, int CH> ...
;     ...
;   if (MODE == 2) {
; #pragma unroll
;     for (int nq = 0; nq < NQ; ++nq) {
;       const int c = c0 + nq * 16 + fr;
;       const int cs = min(max(c - 8, 0), 48);
; #pragma unroll
;       for (int mk = 0; mk < 4; ++mk)
; #pragma unroll
;         for (int j = 0; j < 4; ++j) {
;           const int x = mk * 16 + fq * 4 + j;
;           dci[nq][mk][j] = min(max(x - c + 15, 0), 30);
;           pen[nq][mk][j] = ((x >= cs) && (x < cs + 16)) ? 0.f : NEGBIG;
;         }
;     }
;   }
;   u32x4 kregA, kregB, kregC, vregA, vregB, vregC;
;   kregB = u32x4{0u, 0u, 0u, 0u}; kregC = kregB; vregB = kregB; vregC = kregB;
;   const int kr0 = tid / KCH, kc0 = tid % KCH;
;   const int kr1 = (tid + 512) / KCH, kc1 = (tid + 512) % KCH;
;   const bool k1on = (KCH == 12) && (tid < 256);
;   const int vd0 = tid >> 3, vc0 = tid & 7;
	v_cmp_lt_u32_e32 vcc, v65, v58
	v_cmp_lt_i32_e64 s[18:19], 0, v49
	v_cmp_lt_i32_e64 s[20:21], 1, v49
	v_cndmask_b32_e64 v124, v207, 0, vcc
	v_cmp_lt_u32_e32 vcc, v64, v59
	v_cmp_lt_i32_e64 s[22:23], 2, v49
	v_lshlrev_b64 v[46:47], 1, v[46:47]
	v_cndmask_b32_e64 v127, v207, 0, vcc
	v_cmp_lt_u32_e32 vcc, v65, v59
	v_lshl_add_u32 v173, v53, 4, 0
	v_mov_b32_e32 v53, v0
	v_cndmask_b32_e64 v126, v207, 0, vcc
	v_cmp_gt_i32_e32 vcc, 1, v48
	s_and_b64 s[82:83], vcc, s[16:17]
	s_add_u32 s2, s2, s24
	s_addc_u32 s3, s3, 0
	v_lshl_add_u32 v48, s45, 6, v54
	s_add_u32 s2, s2, 0x15314000
	v_add_u32_e32 v54, 64, v48
	s_addc_u32 s3, s3, 0
	s_add_i32 s4, s9, s4
	v_ashrrev_i32_e32 v55, 31, v54
	s_ashr_i32 s5, s4, 31
	v_lshlrev_b64 v[54:55], 11, v[54:55]
	s_lshl_b64 s[4:5], s[4:5], 19
	v_lshl_add_u64 v[54:55], s[2:3], 0, v[54:55]
	v_ashrrev_i32_e32 v49, 31, v48
	s_add_u32 s4, s4, 0x19314200
	v_lshl_add_u64 v[128:129], v[54:55], 0, v[46:47]
	v_lshlrev_b64 v[54:55], 11, v[48:49]
	s_addc_u32 s5, s5, 0
	v_and_b32_e32 v49, 7, v52
	v_lshl_add_u64 v[44:45], s[4:5], 0, v[44:45]
	v_lshlrev_b32_e32 v52, 4, v49
	v_lshl_add_u64 v[44:45], v[44:45], 0, v[52:53]
	v_lshl_add_u64 v[132:133], v[44:45], 0, s[0:1]
	v_subrev_u32_e32 v44, 64, v48
	v_ashrrev_i32_e32 v45, 31, v44
	v_lshlrev_b64 v[44:45], 11, v[44:45]
	v_lshl_add_u64 v[54:55], s[2:3], 0, v[54:55]
	v_lshl_add_u64 v[44:45], s[2:3], 0, v[44:45]
	v_lshl_add_u64 v[130:131], v[54:55], 0, v[46:47]
	v_lshl_add_u64 v[134:135], v[44:45], 0, v[46:47]
	v_add_u32_e32 v45, v51, v50
	v_lshlrev_b32_e32 v46, 6, v56
	v_add_u32_e32 v44, 1, v148
	v_sub_u32_e32 v45, v45, v46
	v_sub_u32_e32 v47, v44, v45
	v_max_i32_e32 v47, -15, v47
	v_add_u32_e32 v47, 15, v47
	v_min_u32_e32 v47, 30, v47
	s_movk_i32 s0, 0x7c
	s_mul_i32 s25, s45, 0x7c
	v_lshlrev_b32_e32 v175, 2, v47
	v_mul_lo_u32 v47, v56, s0
	v_sub_u32_e32 v47, s25, v47
	v_subrev_u32_e32 v47, s33, v47
	v_add_u32_e32 v176, 0, v47
	v_sub_u32_e32 v47, v69, v45
	v_max_i32_e32 v47, -15, v47
	v_add_u32_e32 v47, 15, v47
	v_min_u32_e32 v47, 30, v47
	v_lshlrev_b32_e32 v177, 2, v47
	v_sub_u32_e32 v47, v60, v45
	v_max_i32_e32 v47, -15, v47
	v_add_u32_e32 v47, 15, v47
	v_min_u32_e32 v47, 30, v47
	v_lshlrev_b32_e32 v178, 2, v47
	v_sub_u32_e32 v47, v61, v45
	v_max_i32_e32 v47, -15, v47
	v_add_u32_e32 v47, 15, v47
	v_min_u32_e32 v47, 30, v47
	v_lshlrev_b32_e32 v179, 2, v47
	v_add_u32_e32 v47, 17, v148
	v_sub_u32_e32 v48, v47, v45
	v_max_i32_e32 v48, -15, v48
	v_add_u32_e32 v48, 15, v48
	v_min_u32_e32 v48, 30, v48
	v_lshlrev_b32_e32 v180, 2, v48
	v_add_u32_e32 v48, 18, v148
	v_sub_u32_e32 v49, v48, v45
	v_max_i32_e32 v49, -15, v49
	v_add_u32_e32 v49, 15, v49
	v_min_u32_e32 v49, 30, v49
	v_lshlrev_b32_e32 v181, 2, v49
	v_add_u32_e32 v49, 19, v148
	v_sub_u32_e32 v52, v49, v45
	v_max_i32_e32 v52, -15, v52
	v_add_u32_e32 v52, 15, v52
	v_min_u32_e32 v52, 30, v52
	v_lshlrev_b32_e32 v182, 2, v52
	v_sub_u32_e32 v52, v148, v45
	v_add_u32_e32 v53, 32, v52
	v_max_i32_e32 v53, -15, v53
	v_add_u32_e32 v53, 15, v53
	v_min_u32_e32 v53, 30, v53
	v_lshlrev_b32_e32 v183, 2, v53
	v_add_u32_e32 v53, 33, v52
	v_max_i32_e32 v53, -15, v53
	v_add_u32_e32 v53, 15, v53
	v_min_u32_e32 v53, 30, v53
	v_lshlrev_b32_e32 v184, 2, v53
	v_add_u32_e32 v53, 34, v52
	v_max_i32_e32 v53, -15, v53
	v_add_u32_e32 v53, 15, v53
	v_min_u32_e32 v53, 30, v53
	v_lshlrev_b32_e32 v185, 2, v53
	v_add_u32_e32 v53, 35, v52
	v_max_i32_e32 v53, -15, v53
	v_add_u32_e32 v53, 15, v53
	v_min_u32_e32 v53, 30, v53
	v_lshlrev_b32_e32 v186, 2, v53
	v_sub_u32_e32 v53, v63, v45
	v_add_u32_e32 v53, 15, v53
	v_min_u32_e32 v53, 30, v53
	v_lshlrev_b32_e32 v187, 2, v53
	v_sub_u32_e32 v53, v62, v45
	v_add_u32_e32 v53, 15, v53
	v_min_u32_e32 v53, 30, v53
	v_lshlrev_b32_e32 v188, 2, v53
	v_sub_u32_e32 v53, v65, v45
	v_sub_u32_e32 v45, v64, v45
	v_add_u32_e32 v45, 15, v45
	v_add_u32_e32 v53, 15, v53
	v_min_u32_e32 v45, 30, v45
	v_min_u32_e32 v53, 30, v53
	v_lshlrev_b32_e32 v190, 2, v45
	v_add_u32_e32 v45, -16, v46
	v_lshlrev_b32_e32 v189, 2, v53
	v_or_b32_e32 v53, v45, v148
	v_sub_u32_e32 v53, v53, v50
	v_sub_u32_e32 v53, v53, v51
	v_max_i32_e32 v53, -15, v53
	v_or_b32_e32 v44, v44, v46
	v_add_u32_e32 v53, 15, v53
	v_sub_u32_e32 v44, v44, v50
	v_min_u32_e32 v53, 30, v53
	v_sub_u32_e32 v44, v44, v51
	v_lshlrev_b32_e32 v191, 2, v53
	v_or_b32_e32 v53, v46, v148
	v_max_i32_e32 v44, -15, v44
	v_sub_u32_e32 v54, v53, v50
	v_add_u32_e32 v44, 15, v44
	v_sub_u32_e32 v54, v54, v51
	v_min_u32_e32 v44, 30, v44
	v_lshlrev_b32_e32 v196, 2, v44
	v_add_u32_e32 v44, 2, v54
	v_max_i32_e32 v44, -15, v44
	v_add_u32_e32 v44, 15, v44
	v_min_u32_e32 v44, 30, v44
	v_lshlrev_b32_e32 v197, 2, v44
	v_add_u32_e32 v44, 3, v54
	v_max_i32_e32 v44, -15, v44
	v_add_u32_e32 v44, 15, v44
	v_min_u32_e32 v44, 30, v44
	v_lshlrev_b32_e32 v198, 2, v44
	v_or_b32_e32 v44, v61, v46
	v_sub_u32_e32 v44, v44, v50
	v_sub_u32_e32 v44, v44, v51
	v_max_i32_e32 v44, -15, v44
	v_add_u32_e32 v44, 15, v44
	v_min_u32_e32 v44, 30, v44
	v_lshlrev_b32_e32 v199, 2, v44
	v_or_b32_e32 v44, v47, v46
	v_sub_u32_e32 v44, v44, v50
	v_sub_u32_e32 v44, v44, v51
	v_max_i32_e32 v44, -15, v44
	v_add_u32_e32 v44, 15, v44
	v_min_u32_e32 v44, 30, v44
	v_lshlrev_b32_e32 v200, 2, v44
	v_or_b32_e32 v44, v48, v46
	v_sub_u32_e32 v44, v44, v50
	v_sub_u32_e32 v44, v44, v51
	v_max_i32_e32 v44, -15, v44
	v_add_u32_e32 v44, 15, v44
	v_min_u32_e32 v44, 30, v44
	v_lshlrev_b32_e32 v201, 2, v44
	v_or_b32_e32 v44, v49, v46
	v_sub_u32_e32 v44, v44, v50
	v_sub_u32_e32 v44, v44, v51
	v_add_u32_e32 v55, -15, v54
	v_max_i32_e32 v44, -15, v44
	v_max_i32_e32 v55, -15, v55
	v_add_u32_e32 v44, 15, v44
	v_add_u32_e32 v55, 15, v55
	v_min_u32_e32 v44, 30, v44
; template <int DQK, int NQ, int MODE, int CH> ...
;     ...
;   if (MODE == 2) {
; #pragma unroll
;     for (int nq = 0; nq < NQ; ++nq) {
;       const int c = c0 + nq * 16 + fr;
;       const int cs = min(max(c - 8, 0), 48);
; #pragma unroll
;       for (int mk = 0; mk < 4; ++mk)
; #pragma unroll
;         for (int j = 0; j < 4; ++j) {
;           const int x = mk * 16 + fq * 4 + j;
;           dci[nq][mk][j] = min(max(x - c + 15, 0), 30);
;           pen[nq][mk][j] = ((x >= cs) && (x < cs + 16)) ? 0.f : NEGBIG;
;         }
;     }
;   }
;     ...
;   __syncthreads();
;   LOAD_CHUNK(kt_lo);
;   STORE_CHUNK(0);
;   __syncthreads();
	v_min_u32_e32 v55, 30, v55
	v_lshlrev_b32_e32 v202, 2, v44
	v_add_u32_e32 v44, 47, v54
	v_lshlrev_b32_e32 v192, 2, v55
	v_or_b32_e32 v55, v45, v69
	v_or_b32_e32 v45, v45, v60
	v_min_u32_e32 v44, 30, v44
	v_sub_u32_e32 v45, v45, v50
	v_lshlrev_b32_e32 v203, 2, v44
	v_add_u32_e32 v44, 50, v54
	v_sub_u32_e32 v45, v45, v51
	v_min_u32_e32 v44, 30, v44
	v_max_i32_e32 v45, -15, v45
	v_lshlrev_b32_e32 v204, 2, v44
	v_add_u32_e32 v44, 49, v54
	v_sub_u32_e32 v55, v55, v50
	v_add_u32_e32 v45, 15, v45
	v_min_u32_e32 v44, 30, v44
	v_sub_u32_e32 v55, v55, v51
	v_min_u32_e32 v45, 30, v45
	v_lshlrev_b32_e32 v205, 2, v44
	v_or_b32_e32 v44, 48, v53
	v_max_i32_e32 v55, -15, v55
	v_lshlrev_b32_e32 v194, 2, v45
	v_max_i32_e32 v45, -15, v52
	v_sub_u32_e32 v44, v44, v50
	v_add_u32_e32 v55, 15, v55
	v_add_u32_e32 v45, 15, v45
	v_sub_u32_e32 v44, v44, v51
	v_min_u32_e32 v55, 30, v55
	v_min_u32_e32 v45, 30, v45
	v_min_u32_e32 v44, 30, v44
	v_mov_b32_e32 v68, v0
	v_mov_b32_e32 v69, v0
	v_mov_b32_e32 v70, v0
	v_mov_b32_e32 v71, v0
	v_mov_b32_e32 v1, v0
	v_mul_u32_u24_e32 v174, 0x90, v50
	v_lshlrev_b32_e32 v193, 2, v55
	v_lshlrev_b32_e32 v195, 2, v45
	v_lshlrev_b32_e32 v206, 2, v44
	v_mov_b64_e32 v[56:57], v[68:69]
	v_mov_b64_e32 v[74:75], v[70:71]
	v_mov_b64_e32 v[52:53], v[68:69]
	v_mov_b64_e32 v[64:65], v[68:69]
	v_mov_b64_e32 v[48:49], v[68:69]
	v_mov_b64_e32 v[60:61], v[68:69]
	v_mov_b64_e32 v[44:45], v[68:69]
	v_add_u32_e32 v172, 8, v155
	s_mov_b32 s61, 0
	s_mov_b32 s0, 5
	v_mov_b32_e32 v208, 0xf149f2ca
	v_mov_b64_e32 v[58:59], v[70:71]
	v_mov_b64_e32 v[72:73], v[68:69]
	v_mov_b64_e32 v[54:55], v[70:71]
	v_mov_b64_e32 v[66:67], v[70:71]
	v_mov_b64_e32 v[50:51], v[70:71]
	v_mov_b64_e32 v[62:63], v[70:71]
	v_mov_b64_e32 v[46:47], v[70:71]
	v_mov_b64_e32 v[136:137], v[0:1]
	s_waitcnt vmcnt(2)
	ds_write_b128 v221, v[20:23]
	s_waitcnt vmcnt(0)
	ds_write2_b64 v222, v[24:25], v[26:27] offset1:2
	ds_write_b128 v221, v[28:31] offset:9216
	ds_write2_b64 v223, v[32:33], v[34:35] offset0:128 offset1:130
	ds_write_b128 v221, v[36:39] offset:18432
	ds_write2_b64 v224, v[40:41], v[42:43] offset1:2
	s_and_saveexec_b64 vcc, s[66:67]
	v_mul_f32_e32 v225, 0x3fb8aa3b, v225
	v_lshlrev_b32_e32 v226, 2, v214
	v_add_u32_e32 v226, 0x1c000, v226
	ds_write_b32 v226, v225
	s_mov_b64 exec, vcc
	s_waitcnt lgkmcnt(0)
	s_barrier
	v_cndmask_b32_e64 v248, v179, v195, s[82:83]
	v_cndmask_b32_e64 v249, v183, v179, s[82:83]
	v_cndmask_b32_e64 v250, v187, v183, s[82:83]
	v_cndmask_b32_e64 v251, v195, v191, s[82:83]
	v_cndmask_b32_e64 v252, v199, v195, s[82:83]
	v_cndmask_b32_e64 v253, v203, v199, s[82:83]
	v_min_u32_e32 v248, 0x6c, v248
	v_min_u32_e32 v249, 0x6c, v249
	v_min_u32_e32 v250, 0x6c, v250
	v_min_u32_e32 v251, 0x6c, v251
	v_min_u32_e32 v252, 0x6c, v252
	v_min_u32_e32 v253, 0x6c, v253
	v_add3_u32 v248, v248, v176, s15
	v_add3_u32 v249, v249, v176, s15
	v_add3_u32 v250, v250, v176, s15
	v_add3_u32 v251, v251, v176, s15
	v_add3_u32 v252, v252, v176, s15
	v_add3_u32 v253, v253, v176, s15
	v_cndmask_b32_e64 v178, v156, v2, s[82:83]
	v_cndmask_b32_e64 v179, v157, v3, s[82:83]
	v_cndmask_b32_e64 v180, v158, v116, s[82:83]
	v_cndmask_b32_e64 v181, v159, v117, s[82:83]
	v_cndmask_b32_e64 v182, v160, v156, s[82:83]
	v_cndmask_b32_e64 v183, v161, v157, s[82:83]
	v_cndmask_b32_e64 v184, v162, v158, s[82:83]
	v_cndmask_b32_e64 v185, v163, v159, s[82:83]
	v_cndmask_b32_e64 v186, v120, v160, s[82:83]
	v_cndmask_b32_e64 v187, v121, v161, s[82:83]
	v_cndmask_b32_e64 v188, v124, v162, s[82:83]
	v_cndmask_b32_e64 v189, v125, v163, s[82:83]
	v_cndmask_b32_e64 v190, v164, v114, s[82:83]
	v_cndmask_b32_e64 v191, v165, v115, s[82:83]
	v_cndmask_b32_e64 v192, v166, v118, s[82:83]
	v_cndmask_b32_e64 v193, v167, v119, s[82:83]
	v_cndmask_b32_e64 v194, v168, v164, s[82:83]
	v_cndmask_b32_e64 v195, v169, v165, s[82:83]
	v_cndmask_b32_e64 v196, v170, v166, s[82:83]
	v_cndmask_b32_e64 v197, v171, v167, s[82:83]
	v_cndmask_b32_e64 v198, v122, v168, s[82:83]
	v_cndmask_b32_e64 v199, v123, v169, s[82:83]
	v_cndmask_b32_e64 v200, v126, v170, s[82:83]
	v_cndmask_b32_e64 v201, v127, v171, s[82:83]
	v_mul_f32_e32 v178, 0x40b17218, v178
	v_mul_f32_e32 v179, 0x40b17218, v179
	v_mul_f32_e32 v180, 0x40b17218, v180
	v_mul_f32_e32 v181, 0x40b17218, v181
	v_mul_f32_e32 v182, 0x40b17218, v182
	v_mul_f32_e32 v183, 0x40b17218, v183
	v_mul_f32_e32 v184, 0x40b17218, v184
	v_mul_f32_e32 v185, 0x40b17218, v185
	v_mul_f32_e32 v186, 0x40b17218, v186
	v_mul_f32_e32 v187, 0x40b17218, v187
	v_mul_f32_e32 v188, 0x40b17218, v188
	v_mul_f32_e32 v189, 0x40b17218, v189
	v_mul_f32_e32 v190, 0x40b17218, v190
	v_mul_f32_e32 v191, 0x40b17218, v191
	v_mul_f32_e32 v192, 0x40b17218, v192
	v_mul_f32_e32 v193, 0x40b17218, v193
	v_mul_f32_e32 v194, 0x40b17218, v194
	v_mul_f32_e32 v195, 0x40b17218, v195
	v_mul_f32_e32 v196, 0x40b17218, v196
	v_mul_f32_e32 v197, 0x40b17218, v197
	v_mul_f32_e32 v198, 0x40b17218, v198
	v_mul_f32_e32 v199, 0x40b17218, v199
	v_mul_f32_e32 v200, 0x40b17218, v200
	v_mul_f32_e32 v201, 0x40b17218, v201
	v_mov_b32_e32 v202, 0x900
	v_add_u32_e32 v203, 0xd800, v174
	v_cndmask_b32_e64 v202, v202, 0, s[82:83]
	v_add_u32_e32 v202, v202, v174
	v_readfirstlane_b32 s98, v214
	s_nop 3
	s_cmp_ge_u32 s98, 0x100
	s_cbranch_scc0 .Lprio_done_nat
	s_setprio 1
.Lprio_done_nat:
	s_branch .LBB0_1531
.Lna_skip_fill:
	s_waitcnt vmcnt(2)
	ds_write_b128 v221, v[20:23]
	s_waitcnt vmcnt(0)
	ds_write2_b64 v222, v[24:25], v[26:27] offset1:2
	ds_write_b128 v221, v[28:31] offset:9216
	ds_write2_b64 v223, v[32:33], v[34:35] offset0:128 offset1:130
	ds_write_b128 v221, v[36:39] offset:18432
	ds_write2_b64 v224, v[40:41], v[42:43] offset1:2
	s_and_saveexec_b64 vcc, s[66:67]
	v_mul_f32_e32 v225, 0x3fb8aa3b, v225
	v_lshlrev_b32_e32 v226, 2, v214
	v_add_u32_e32 v226, 0x1c000, v226
	ds_write_b32 v226, v225
	s_mov_b64 exec, vcc
	s_waitcnt lgkmcnt(0)
	s_barrier
	s_branch .LBB0_1676

; template <int DQK, int NQ, int MODE, int CH> ...
;     ...
;         __builtin_amdgcn_s_setprio(0);
;       }
;     }
;     if (kt0 + CH < kt_hi) STORE_CHUNK(buf ^ 1);
;     buf ^= 1;
;     __syncthreads();
;   }
.LBB0_1677:
	s_setprio 0
	v_readlane_b32 s82, v242, 10
	v_readlane_b32 s83, v242, 11
